# K-loop back-edge rotation: loop counter/exit test and next-iteration scalar head run before the loop-back barrier; exit path has own barrier copy (on v38)
# baseline (speedup 1.0000x reference)
; #define PG8_STAGE(bufoff, gbase, voff) do { _Pragma("unroll") for (int _i = 0; _i < 2; ++_i) \
;         __builtin_amdgcn_global_load_lds((const unsigned*)((const char*)(gbase) + (voff)[_i]), (PG8_LAS unsigned*)(lds + (bufoff) + ldsw + _i * 8192), 16, 0, 0); } while (0)
; #define PG8_LDA(dst, b, h) do { _Pragma("unroll") for (int m = 0; m < 4; ++m) _Pragma("unroll") for (int k = 0; k < 2; ++k) dst[m][k] = *(const PG8_LAS bf16x8*)(lds + PG8_SA(b, h) + aoff + m * 2048 + k * 1024); } while (0)
; #define PG8_LDB(dst, b, h) do { _Pragma("unroll") for (int n = 0; n < 2; ++n) _Pragma("unroll") for (int k = 0; k < 2; ++k) dst[n][k] = *(const PG8_LAS bf16x8*)(lds + PG8_SB(b, h) + boff + n * 2048 + k * 1024); } while (0)
; #define PG8_SCHED __builtin_amdgcn_sched_barrier(0)
; template <class Epi, class Sched, bool ALIGN_EPI = false, bool SP2 = false>
; __device__ __forceinline__ void gemm_phase(PG8_LAS unsigned char* lds, const Gemm g, const Sched& S, const Epi& E, const int tid) {
;     ...
;         for (int t = 0; t < nt; t += 2) {
;             const bool last = (t == nt - 2);
;             const char* a1 = cA + (size_t)(t + 1) * kstep;
;             const char* a2 = last ? nA : cA + (size_t)(t + 2) * kstep; const char* b2 = last ? nB : cB + (size_t)(t + 2) * kstep;
;             const char* a3 = a2 + kstep; const char* b3 = b2 + kstep;
;             if (last && has_next) S.a_ready(nxt);
;             if constexpr (SP2) {
;             PG8_LDB(B0, 0, 0); PG8_LDB(B1, 0, 1); PG8_SCHED; PG8_LDA(At, 0, 0); PG8_STAGE(PG8_SA(1, 1), a1 + hstepA, voffA);
.LBB0_35:
	s_add_u32 s18, s8, 0xfff80080
	s_addc_u32 s19, s9, -1
	s_add_i32 s36, 0, 0x10000
	s_cmp_eq_u32 s31, 12
	s_cselect_b32 s23, s26, s19
	s_cselect_b32 s22, s27, s18
	s_cselect_b32 s19, s13, s30
	s_cselect_b32 s18, s28, s29
	s_cmp_eq_u32 s31, -2
	s_cselect_b32 s99, 1, 0
	s_cmp_eq_u32 s89, 1
	s_cselect_b32 s99, 0, s99
	s_add_i32 s38, 0, 0x14000
.Lkl_up_body:
	v_add_u32_e32 v128, s36, v155
	ds_read_b128 v[148:151], v128
	ds_read_b128 v[158:161], v128 offset:1024
	ds_read_b128 v[162:165], v128 offset:2048
	ds_read_b128 v[188:191], v128 offset:3072
	v_add_u32_e32 v128, s38, v155
	ds_read_b128 v[192:195], v128
	ds_read_b128 v[196:199], v128 offset:1024
	ds_read_b128 v[200:203], v128 offset:2048
	ds_read_b128 v[204:207], v128 offset:3072
	v_lshl_add_u64 v[166:167], s[8:9], 0, v[144:145]
	s_add_i32 m0, s69, 0xc000
	ds_read_b128 v[208:211], v157
	ds_read_b128 v[212:215], v157 offset:1024
	ds_read_b128 v[216:219], v157 offset:2048
	ds_read_b128 v[220:223], v157 offset:3072
	ds_read_b128 v[224:227], v157 offset:4096
	ds_read_b128 v[228:231], v157 offset:5120
	ds_read_b128 v[232:235], v157 offset:6144
	ds_read_b128 v[236:239], v157 offset:7168
	global_load_lds_dwordx4 v[166:167], off
	v_lshl_add_u64 v[166:167], s[8:9], 0, v[146:147]
	s_add_i32 m0, s69, 0xe000
	s_nop 0
	global_load_lds_dwordx4 v[166:167], off
	s_cmp_eq_u32 s99, 1
	s_cbranch_scc1 .Lkw_up_0
	s_waitcnt vmcnt(8)

; #define PG8_STAGE(bufoff, gbase, voff) do { _Pragma("unroll") for (int _i = 0; _i < 2; ++_i) \
;         __builtin_amdgcn_global_load_lds((const unsigned*)((const char*)(gbase) + (voff)[_i]), (PG8_LAS unsigned*)(lds + (bufoff) + ldsw + _i * 8192), 16, 0, 0); } while (0)
; #define PG8_LDA(dst, b, h) do { _Pragma("unroll") for (int m = 0; m < 4; ++m) _Pragma("unroll") for (int k = 0; k < 2; ++k) dst[m][k] = *(const PG8_LAS bf16x8*)(lds + PG8_SA(b, h) + aoff + m * 2048 + k * 1024); } while (0)
; #define PG8_LDB(dst, b, h) do { _Pragma("unroll") for (int n = 0; n < 2; ++n) _Pragma("unroll") for (int k = 0; k < 2; ++k) dst[n][k] = *(const PG8_LAS bf16x8*)(lds + PG8_SB(b, h) + boff + n * 2048 + k * 1024); } while (0)
; #define PG8_MMA(ai, bj, At, Bt) do { __builtin_amdgcn_s_setprio(1); _Pragma("unroll") for (int m = 0; m < 4; ++m) _Pragma("unroll") for (int n = 0; n < 2; ++n) _Pragma("unroll") for (int k = 0; k < 2; ++k) \
;         acc[ai][bj][m][n] = __builtin_amdgcn_mfma_f32_16x16x32_bf16(Bt[n][k], At[m][k], acc[ai][bj][m][n], 0, 0, 0); __builtin_amdgcn_s_setprio(0); } while (0)
; #define PG8_WAIT_V(n) asm volatile("s_waitcnt vmcnt(" #n ")" ::: "memory")
; #define PG8_WAIT_L(n) asm volatile("s_waitcnt lgkmcnt(" #n ")" ::: "memory")
; template <class Epi, class Sched, bool ALIGN_EPI = false, bool SP2 = false>
; __device__ __forceinline__ void gemm_phase(PG8_LAS unsigned char* lds, const Gemm g, const Sched& S, const Epi& E, const int tid) {
;     ...
;             PG8_WAIT_V(8); PG8_WAIT_L(0); PG8_BAR; PG8_MMA(0, 0, At, B0); PG8_MMA(0, 1, At, B1); PG8_BAR; PG8_SCHED;
;             PG8_LDA(At, 0, 1); PG8_STAGE(PG8_SB(0, 0), b2, voffB); PG8_STAGE(PG8_SB(0, 1), b2 + hstepB, voffB); PG8_STAGE(PG8_SA(0, 0), a2, voffA);
;             PG8_WAIT_V(8); PG8_WAIT_L(0); PG8_BAR; PG8_MMA(1, 0, At, B0); PG8_MMA(1, 1, At, B1); PG8_BAR; PG8_SCHED;
;             PG8_LDB(B0, 1, 0); PG8_LDB(B1, 1, 1); PG8_SCHED; PG8_LDA(At, 1, 0); PG8_STAGE(PG8_SA(0, 1), a2 + hstepA, voffA);
;             PG8_WAIT_V(8); PG8_WAIT_L(0); PG8_BAR; PG8_MMA(0, 0, At, B0); PG8_MMA(0, 1, At, B1); PG8_BAR; PG8_SCHED;
;             PG8_LDA(At, 1, 1); PG8_STAGE(PG8_SB(1, 0), b3, voffB); PG8_STAGE(PG8_SB(1, 1), b3 + hstepB, voffB); PG8_STAGE(PG8_SA(1, 0), a3, voffA);
;             PG8_WAIT_V(8); PG8_WAIT_L(0); PG8_BAR; PG8_MMA(1, 0, At, B0); PG8_MMA(1, 1, At, B1); PG8_BAR; PG8_SCHED;
.Lkw_up_1:
	s_waitcnt lgkmcnt(0)
	s_barrier
	s_setprio 1
	s_waitcnt lgkmcnt(0)
	v_mfma_f32_16x16x32_bf16 v[60:63], v[148:151], v[208:211], v[60:63]
	v_mfma_f32_16x16x32_bf16 v[56:59], v[162:165], v[208:211], v[56:59]
	v_mfma_f32_16x16x32_bf16 v[44:47], v[148:151], v[216:219], v[44:47]
	v_mfma_f32_16x16x32_bf16 v[40:43], v[162:165], v[216:219], v[40:43]
	v_mfma_f32_16x16x32_bf16 v[28:31], v[148:151], v[224:227], v[28:31]
	v_mfma_f32_16x16x32_bf16 v[24:27], v[162:165], v[224:227], v[24:27]
	v_mfma_f32_16x16x32_bf16 v[12:15], v[148:151], v[232:235], v[12:15]
	v_mfma_f32_16x16x32_bf16 v[8:11], v[162:165], v[232:235], v[8:11]
	v_mfma_f32_16x16x32_bf16 v[60:63], v[158:161], v[212:215], v[60:63]
	v_mfma_f32_16x16x32_bf16 v[56:59], v[188:191], v[212:215], v[56:59]
	v_mfma_f32_16x16x32_bf16 v[44:47], v[158:161], v[220:223], v[44:47]
	v_mfma_f32_16x16x32_bf16 v[40:43], v[188:191], v[220:223], v[40:43]
	v_mfma_f32_16x16x32_bf16 v[28:31], v[158:161], v[228:231], v[28:31]
	v_mfma_f32_16x16x32_bf16 v[24:27], v[188:191], v[228:231], v[24:27]
	v_mfma_f32_16x16x32_bf16 v[12:15], v[158:161], v[236:239], v[12:15]
	v_mfma_f32_16x16x32_bf16 v[8:11], v[188:191], v[236:239], v[8:11]
	s_setprio 0
	s_setprio 1
	v_mfma_f32_16x16x32_bf16 v[52:55], v[192:195], v[208:211], v[52:55]
	v_mfma_f32_16x16x32_bf16 v[48:51], v[200:203], v[208:211], v[48:51]
	v_mfma_f32_16x16x32_bf16 v[36:39], v[192:195], v[216:219], v[36:39]
	v_mfma_f32_16x16x32_bf16 v[32:35], v[200:203], v[216:219], v[32:35]
	v_mfma_f32_16x16x32_bf16 v[20:23], v[192:195], v[224:227], v[20:23]
	v_mfma_f32_16x16x32_bf16 v[16:19], v[200:203], v[224:227], v[16:19]
	v_mfma_f32_16x16x32_bf16 v[4:7], v[192:195], v[232:235], v[4:7]
	v_mfma_f32_16x16x32_bf16 v[0:3], v[200:203], v[232:235], v[0:3]
	v_mfma_f32_16x16x32_bf16 v[52:55], v[196:199], v[212:215], v[52:55]
	v_mfma_f32_16x16x32_bf16 v[48:51], v[204:207], v[212:215], v[48:51]
	v_mfma_f32_16x16x32_bf16 v[36:39], v[196:199], v[220:223], v[36:39]
	v_mfma_f32_16x16x32_bf16 v[32:35], v[204:207], v[220:223], v[32:35]
	v_mfma_f32_16x16x32_bf16 v[20:23], v[196:199], v[228:231], v[20:23]
	v_mfma_f32_16x16x32_bf16 v[16:19], v[204:207], v[228:231], v[16:19]
	v_mfma_f32_16x16x32_bf16 v[4:7], v[196:199], v[236:239], v[4:7]
	v_mfma_f32_16x16x32_bf16 v[0:3], v[204:207], v[236:239], v[0:3]
	s_setprio 0
	s_barrier
	s_add_i32 s36, 0, 0x18000
	v_add_u32_e32 v128, s36, v155
	s_add_i32 s37, 0, 0x1c000
	ds_read_b128 v[148:151], v128
	ds_read_b128 v[158:161], v128 offset:1024
	ds_read_b128 v[162:165], v128 offset:2048
	ds_read_b128 v[188:191], v128 offset:3072
	v_add_u32_e32 v128, s37, v155
	ds_read_b128 v[192:195], v128
	ds_read_b128 v[196:199], v128 offset:1024
	ds_read_b128 v[200:203], v128 offset:2048
	ds_read_b128 v[204:207], v128 offset:3072
	s_add_u32 s22, s22, 0x80000
	s_addc_u32 s23, s23, 0
	s_mov_b32 m0, s71
	v_lshl_add_u64 v[246:247], s[22:23], 0, v[142:143]
	ds_read_b128 v[208:211], v157 offset:32768
	ds_read_b128 v[212:215], v157 offset:33792
	ds_read_b128 v[216:219], v157 offset:34816
	ds_read_b128 v[220:223], v157 offset:35840
	ds_read_b128 v[224:227], v157 offset:36864
	ds_read_b128 v[228:231], v157 offset:37888
	ds_read_b128 v[232:235], v157 offset:38912
	ds_read_b128 v[236:239], v157 offset:39936
	global_load_lds_dwordx4 v[246:247], off
	v_lshl_add_u64 v[246:247], s[22:23], 0, v[138:139]
	s_mov_b32 m0, s74
	s_nop 0
	global_load_lds_dwordx4 v[246:247], off
	s_waitcnt vmcnt(8)
	s_waitcnt lgkmcnt(0)
	s_barrier
	s_setprio 1
	s_waitcnt lgkmcnt(0)
	v_mfma_f32_16x16x32_bf16 v[124:127], v[148:151], v[208:211], v[124:127]
	v_mfma_f32_16x16x32_bf16 v[120:123], v[162:165], v[208:211], v[120:123]
	v_mfma_f32_16x16x32_bf16 v[108:111], v[148:151], v[216:219], v[108:111]
	v_mfma_f32_16x16x32_bf16 v[104:107], v[162:165], v[216:219], v[104:107]
	v_mfma_f32_16x16x32_bf16 v[92:95], v[148:151], v[224:227], v[92:95]
	v_mfma_f32_16x16x32_bf16 v[88:91], v[162:165], v[224:227], v[88:91]
	v_mfma_f32_16x16x32_bf16 v[76:79], v[148:151], v[232:235], v[76:79]
	v_mfma_f32_16x16x32_bf16 v[72:75], v[162:165], v[232:235], v[72:75]
	v_mfma_f32_16x16x32_bf16 v[124:127], v[158:161], v[212:215], v[124:127]
	v_mfma_f32_16x16x32_bf16 v[120:123], v[188:191], v[212:215], v[120:123]
	v_mfma_f32_16x16x32_bf16 v[108:111], v[158:161], v[220:223], v[108:111]
	v_mfma_f32_16x16x32_bf16 v[104:107], v[188:191], v[220:223], v[104:107]
	v_mfma_f32_16x16x32_bf16 v[92:95], v[158:161], v[228:231], v[92:95]
	v_mfma_f32_16x16x32_bf16 v[88:91], v[188:191], v[228:231], v[88:91]
	v_mfma_f32_16x16x32_bf16 v[76:79], v[158:161], v[236:239], v[76:79]
	v_mfma_f32_16x16x32_bf16 v[72:75], v[188:191], v[236:239], v[72:75]
	s_setprio 0
	s_setprio 1
	v_mfma_f32_16x16x32_bf16 v[116:119], v[192:195], v[208:211], v[116:119]
	v_mfma_f32_16x16x32_bf16 v[112:115], v[200:203], v[208:211], v[112:115]
	v_mfma_f32_16x16x32_bf16 v[100:103], v[192:195], v[216:219], v[100:103]
	v_mfma_f32_16x16x32_bf16 v[96:99], v[200:203], v[216:219], v[96:99]
	v_mfma_f32_16x16x32_bf16 v[84:87], v[192:195], v[224:227], v[84:87]
	v_mfma_f32_16x16x32_bf16 v[80:83], v[200:203], v[224:227], v[80:83]
	v_mfma_f32_16x16x32_bf16 v[68:71], v[192:195], v[232:235], v[68:71]
	v_mfma_f32_16x16x32_bf16 v[64:67], v[200:203], v[232:235], v[64:67]
	v_mfma_f32_16x16x32_bf16 v[116:119], v[196:199], v[212:215], v[116:119]
	v_mfma_f32_16x16x32_bf16 v[112:115], v[204:207], v[212:215], v[112:115]
	v_mfma_f32_16x16x32_bf16 v[100:103], v[196:199], v[220:223], v[100:103]
	v_mfma_f32_16x16x32_bf16 v[96:99], v[204:207], v[220:223], v[96:99]
	v_mfma_f32_16x16x32_bf16 v[84:87], v[196:199], v[228:231], v[84:87]
	v_mfma_f32_16x16x32_bf16 v[80:83], v[204:207], v[228:231], v[80:83]
	v_mfma_f32_16x16x32_bf16 v[68:71], v[196:199], v[236:239], v[68:71]
	v_mfma_f32_16x16x32_bf16 v[64:67], v[204:207], v[236:239], v[64:67]
	s_setprio 0
	s_barrier
; #define PG8_STAGE(bufoff, gbase, voff) do { _Pragma("unroll") for (int _i = 0; _i < 2; ++_i) \
;         __builtin_amdgcn_global_load_lds((const unsigned*)((const char*)(gbase) + (voff)[_i]), (PG8_LAS unsigned*)(lds + (bufoff) + ldsw + _i * 8192), 16, 0, 0); } while (0)
; #define PG8_LDA(dst, b, h) do { _Pragma("unroll") for (int m = 0; m < 4; ++m) _Pragma("unroll") for (int k = 0; k < 2; ++k) dst[m][k] = *(const PG8_LAS bf16x8*)(lds + PG8_SA(b, h) + aoff + m * 2048 + k * 1024); } while (0)
; #define PG8_MMA(ai, bj, At, Bt) do { __builtin_amdgcn_s_setprio(1); _Pragma("unroll") for (int m = 0; m < 4; ++m) _Pragma("unroll") for (int n = 0; n < 2; ++n) _Pragma("unroll") for (int k = 0; k < 2; ++k) \
;         acc[ai][bj][m][n] = __builtin_amdgcn_mfma_f32_16x16x32_bf16(Bt[n][k], At[m][k], acc[ai][bj][m][n], 0, 0, 0); __builtin_amdgcn_s_setprio(0); } while (0)
; #define PG8_WAIT_V(n) asm volatile("s_waitcnt vmcnt(" #n ")" ::: "memory")
; #define PG8_WAIT_L(n) asm volatile("s_waitcnt lgkmcnt(" #n ")" ::: "memory")
; #define PG8_BAR __builtin_amdgcn_s_barrier()
; #define PG8_SCHED __builtin_amdgcn_sched_barrier(0)
; template <class Epi, class Sched, bool ALIGN_EPI = false, bool SP2 = false>
; __device__ __forceinline__ void gemm_phase(PG8_LAS unsigned char* lds, const Gemm g, const Sched& S, const Epi& E, const int tid) {
;     ...
;         for (int t = 0; t < nt; t += 2) {
;             const bool last = (t == nt - 2);
;             const char* a1 = cA + (size_t)(t + 1) * kstep;
;             const char* a2 = last ? nA : cA + (size_t)(t + 2) * kstep; const char* b2 = last ? nB : cB + (size_t)(t + 2) * kstep;
;             const char* a3 = a2 + kstep; const char* b3 = b2 + kstep;
;             if (last && has_next) S.a_ready(nxt);
;     ...
;             PG8_WAIT_V(8); PG8_WAIT_L(0); PG8_BAR; PG8_MMA(0, 0, At, B0); PG8_MMA(0, 1, At, B1); PG8_BAR; PG8_SCHED;
;             PG8_LDA(At, 1, 1); PG8_STAGE(PG8_SB(1, 0), b3, voffB); PG8_STAGE(PG8_SB(1, 1), b3 + hstepB, voffB); PG8_STAGE(PG8_SA(1, 0), a3, voffA);
;             PG8_WAIT_V(8); PG8_WAIT_L(0); PG8_BAR; PG8_MMA(1, 0, At, B0); PG8_MMA(1, 1, At, B1); PG8_BAR; PG8_SCHED;
	s_add_i32 s22, s36, s68
	v_lshl_add_u64 v[166:167], v[166:167], 0, s[76:77]
	s_mov_b32 m0, s22
	ds_read_b128 v[208:211], v157 offset:49152
	ds_read_b128 v[212:215], v157 offset:50176
	ds_read_b128 v[216:219], v157 offset:51200
	ds_read_b128 v[220:223], v157 offset:52224
	ds_read_b128 v[224:227], v157 offset:53248
	ds_read_b128 v[228:231], v157 offset:54272
	ds_read_b128 v[232:235], v157 offset:55296
	ds_read_b128 v[236:239], v157 offset:56320
	global_load_lds_dwordx4 v[166:167], off
	s_add_i32 m0, s22, 0x2000
	s_add_u32 s18, s18, 0x40080
	v_lshl_add_u64 v[166:167], v[240:241], 0, s[76:77]
	s_addc_u32 s19, s19, 0
	s_add_i32 s22, s37, s68
	global_load_lds_dwordx4 v[166:167], off
	v_lshl_add_u64 v[166:167], s[18:19], 0, v[140:141]
	s_mov_b32 m0, s22
	s_nop 0
	global_load_lds_dwordx4 v[166:167], off
	v_lshl_add_u64 v[166:167], s[18:19], 0, v[136:137]
	s_add_i32 m0, s22, 0x2000
	s_nop 0
	global_load_lds_dwordx4 v[166:167], off
	v_lshl_add_u64 v[166:167], v[242:243], 0, s[76:77]
	s_mov_b32 m0, s84
	s_nop 0
	global_load_lds_dwordx4 v[166:167], off
	v_lshl_add_u64 v[166:167], v[244:245], 0, s[76:77]
	s_mov_b32 m0, s87
	s_nop 0
	global_load_lds_dwordx4 v[166:167], off
	s_waitcnt vmcnt(8)
	s_waitcnt lgkmcnt(0)
	s_barrier
	s_setprio 1
	s_waitcnt lgkmcnt(0)
	v_mfma_f32_16x16x32_bf16 v[60:63], v[148:151], v[208:211], v[60:63]
	v_mfma_f32_16x16x32_bf16 v[56:59], v[162:165], v[208:211], v[56:59]
	v_mfma_f32_16x16x32_bf16 v[44:47], v[148:151], v[216:219], v[44:47]
	v_mfma_f32_16x16x32_bf16 v[40:43], v[162:165], v[216:219], v[40:43]
	v_mfma_f32_16x16x32_bf16 v[28:31], v[148:151], v[224:227], v[28:31]
	v_mfma_f32_16x16x32_bf16 v[24:27], v[162:165], v[224:227], v[24:27]
	v_mfma_f32_16x16x32_bf16 v[12:15], v[148:151], v[232:235], v[12:15]
	v_mfma_f32_16x16x32_bf16 v[8:11], v[162:165], v[232:235], v[8:11]
	v_mfma_f32_16x16x32_bf16 v[60:63], v[158:161], v[212:215], v[60:63]
	v_mfma_f32_16x16x32_bf16 v[56:59], v[188:191], v[212:215], v[56:59]
	v_mfma_f32_16x16x32_bf16 v[44:47], v[158:161], v[220:223], v[44:47]
	v_mfma_f32_16x16x32_bf16 v[40:43], v[188:191], v[220:223], v[40:43]
	v_mfma_f32_16x16x32_bf16 v[28:31], v[158:161], v[228:231], v[28:31]
	v_mfma_f32_16x16x32_bf16 v[24:27], v[188:191], v[228:231], v[24:27]
	v_mfma_f32_16x16x32_bf16 v[12:15], v[158:161], v[236:239], v[12:15]
	v_mfma_f32_16x16x32_bf16 v[8:11], v[188:191], v[236:239], v[8:11]
	s_setprio 0
	s_setprio 1
	v_mfma_f32_16x16x32_bf16 v[52:55], v[192:195], v[208:211], v[52:55]
	v_mfma_f32_16x16x32_bf16 v[48:51], v[200:203], v[208:211], v[48:51]
	v_mfma_f32_16x16x32_bf16 v[36:39], v[192:195], v[216:219], v[36:39]
	v_mfma_f32_16x16x32_bf16 v[32:35], v[200:203], v[216:219], v[32:35]
	v_mfma_f32_16x16x32_bf16 v[20:23], v[192:195], v[224:227], v[20:23]
	v_mfma_f32_16x16x32_bf16 v[16:19], v[200:203], v[224:227], v[16:19]
	v_mfma_f32_16x16x32_bf16 v[4:7], v[192:195], v[232:235], v[4:7]
	v_mfma_f32_16x16x32_bf16 v[0:3], v[200:203], v[232:235], v[0:3]
	v_mfma_f32_16x16x32_bf16 v[52:55], v[196:199], v[212:215], v[52:55]
	v_mfma_f32_16x16x32_bf16 v[48:51], v[204:207], v[212:215], v[48:51]
	v_mfma_f32_16x16x32_bf16 v[36:39], v[196:199], v[220:223], v[36:39]
	v_mfma_f32_16x16x32_bf16 v[32:35], v[204:207], v[220:223], v[32:35]
	v_mfma_f32_16x16x32_bf16 v[20:23], v[196:199], v[228:231], v[20:23]
	v_mfma_f32_16x16x32_bf16 v[16:19], v[204:207], v[228:231], v[16:19]
	v_mfma_f32_16x16x32_bf16 v[4:7], v[196:199], v[236:239], v[4:7]
	v_mfma_f32_16x16x32_bf16 v[0:3], v[204:207], v[236:239], v[0:3]
	s_setprio 0
	s_add_i32 s31, s31, 2
	s_add_u32 s8, s8, 0x100
	s_addc_u32 s9, s9, 0
	s_add_u32 s29, s29, 0x100
	s_addc_u32 s30, s30, 0
	s_cmp_gt_u32 s31, 13
	s_cbranch_scc1 .Lkl_up_exit
	s_add_u32 s18, s8, 0xfff80080
	s_addc_u32 s19, s9, -1
	s_add_i32 s36, 0, 0x10000
	s_cmp_eq_u32 s31, 12
	s_cselect_b32 s23, s26, s19
	s_cselect_b32 s22, s27, s18
	s_cselect_b32 s19, s13, s30
	s_cselect_b32 s18, s28, s29
	s_cmp_eq_u32 s31, -2
	s_cselect_b32 s99, 1, 0
	s_cmp_eq_u32 s89, 1
	s_cselect_b32 s99, 0, s99
	s_add_i32 s38, 0, 0x14000
	s_barrier
	s_branch .Lkl_up_body
.Lkl_up_exit:
	s_barrier
	s_and_b64 vcc, exec, s[10:11]
	s_cbranch_vccz .LBB0_38
	s_barrier

; #define PG8_STAGE(bufoff, gbase, voff) do { _Pragma("unroll") for (int _i = 0; _i < 2; ++_i) \
;         __builtin_amdgcn_global_load_lds((const unsigned*)((const char*)(gbase) + (voff)[_i]), (PG8_LAS unsigned*)(lds + (bufoff) + ldsw + _i * 8192), 16, 0, 0); } while (0)
; #define PG8_LDA(dst, b, h) do { _Pragma("unroll") for (int m = 0; m < 4; ++m) _Pragma("unroll") for (int k = 0; k < 2; ++k) dst[m][k] = *(const PG8_LAS bf16x8*)(lds + PG8_SA(b, h) + aoff + m * 2048 + k * 1024); } while (0)
; #define PG8_LDB(dst, b, h) do { _Pragma("unroll") for (int n = 0; n < 2; ++n) _Pragma("unroll") for (int k = 0; k < 2; ++k) dst[n][k] = *(const PG8_LAS bf16x8*)(lds + PG8_SB(b, h) + boff + n * 2048 + k * 1024); } while (0)
; #define PG8_SCHED __builtin_amdgcn_sched_barrier(0)
; template <class Epi, class Sched, bool ALIGN_EPI = false, bool SP2 = false>
; __device__ __forceinline__ void gemm_phase(PG8_LAS unsigned char* lds, const Gemm g, const Sched& S, const Epi& E, const int tid) {
;     ...
;         for (int t = 0; t < nt; t += 2) {
;             const bool last = (t == nt - 2);
;             const char* a1 = cA + (size_t)(t + 1) * kstep;
;             const char* a2 = last ? nA : cA + (size_t)(t + 2) * kstep; const char* b2 = last ? nB : cB + (size_t)(t + 2) * kstep;
;             const char* a3 = a2 + kstep; const char* b3 = b2 + kstep;
;             if (last && has_next) S.a_ready(nxt);
;             if constexpr (SP2) {
;             PG8_LDB(B0, 0, 0); PG8_LDB(B1, 0, 1); PG8_SCHED; PG8_LDA(At, 0, 0); PG8_STAGE(PG8_SA(1, 1), a1 + hstepA, voffA);
.LBB0_468:
	s_add_i32 s47, s46, 2
	s_add_u32 s48, s8, 0x80
	s_addc_u32 s49, s9, 0
	s_add_i32 s50, 0, 0x10000
	s_cmp_eq_u32 s30, s46
	s_cselect_b32 s93, s75, s49
	s_cselect_b32 s92, s74, s48
	s_cselect_b32 s49, s42, s45
	s_cselect_b32 s48, s43, s44
	s_cmp_eq_u32 s47, 2
	s_cselect_b32 s99, 1, 0
	s_cmp_eq_u32 s29, 1
	s_cselect_b32 s99, 0, s99
	s_add_i32 s46, 0, 0x14000
.Lkl_pl_body:
	v_add_u32_e32 v128, s50, v155
	ds_read_b128 v[148:151], v128
	ds_read_b128 v[158:161], v128 offset:1024
	ds_read_b128 v[162:165], v128 offset:2048
	ds_read_b128 v[188:191], v128 offset:3072
	v_add_u32_e32 v128, s46, v155
	ds_read_b128 v[192:195], v128
	ds_read_b128 v[196:199], v128 offset:1024
	ds_read_b128 v[200:203], v128 offset:2048
	ds_read_b128 v[204:207], v128 offset:3072
	v_lshl_add_u64 v[166:167], s[8:9], 0, v[144:145]
	s_add_i32 m0, s72, 0xc000
	ds_read_b128 v[208:211], v157
	ds_read_b128 v[212:215], v157 offset:1024
	ds_read_b128 v[216:219], v157 offset:2048
	ds_read_b128 v[220:223], v157 offset:3072
	ds_read_b128 v[224:227], v157 offset:4096
	ds_read_b128 v[228:231], v157 offset:5120
	ds_read_b128 v[232:235], v157 offset:6144
	ds_read_b128 v[236:239], v157 offset:7168
	global_load_lds_dwordx4 v[166:167], off
	v_lshl_add_u64 v[166:167], s[8:9], 0, v[146:147]
	s_add_i32 m0, s72, 0xe000
	s_nop 0
	global_load_lds_dwordx4 v[166:167], off
	s_cmp_eq_u32 s99, 1
	s_cbranch_scc1 .Lkw_pl_0
	s_waitcnt vmcnt(8)

; #define PG8_STAGE(bufoff, gbase, voff) do { _Pragma("unroll") for (int _i = 0; _i < 2; ++_i) \
;         __builtin_amdgcn_global_load_lds((const unsigned*)((const char*)(gbase) + (voff)[_i]), (PG8_LAS unsigned*)(lds + (bufoff) + ldsw + _i * 8192), 16, 0, 0); } while (0)
; #define PG8_LDA(dst, b, h) do { _Pragma("unroll") for (int m = 0; m < 4; ++m) _Pragma("unroll") for (int k = 0; k < 2; ++k) dst[m][k] = *(const PG8_LAS bf16x8*)(lds + PG8_SA(b, h) + aoff + m * 2048 + k * 1024); } while (0)
; #define PG8_LDB(dst, b, h) do { _Pragma("unroll") for (int n = 0; n < 2; ++n) _Pragma("unroll") for (int k = 0; k < 2; ++k) dst[n][k] = *(const PG8_LAS bf16x8*)(lds + PG8_SB(b, h) + boff + n * 2048 + k * 1024); } while (0)
; #define PG8_MMA(ai, bj, At, Bt) do { __builtin_amdgcn_s_setprio(1); _Pragma("unroll") for (int m = 0; m < 4; ++m) _Pragma("unroll") for (int n = 0; n < 2; ++n) _Pragma("unroll") for (int k = 0; k < 2; ++k) \
;         acc[ai][bj][m][n] = __builtin_amdgcn_mfma_f32_16x16x32_bf16(Bt[n][k], At[m][k], acc[ai][bj][m][n], 0, 0, 0); __builtin_amdgcn_s_setprio(0); } while (0)
; #define PG8_WAIT_V(n) asm volatile("s_waitcnt vmcnt(" #n ")" ::: "memory")
; #define PG8_WAIT_L(n) asm volatile("s_waitcnt lgkmcnt(" #n ")" ::: "memory")
; #define PG8_BAR __builtin_amdgcn_s_barrier()
; #define PG8_SCHED __builtin_amdgcn_sched_barrier(0)
; template <class Epi, class Sched, bool ALIGN_EPI = false, bool SP2 = false>
; __device__ __forceinline__ void gemm_phase(PG8_LAS unsigned char* lds, const Gemm g, const Sched& S, const Epi& E, const int tid) {
;     ...
;             PG8_WAIT_V(8); PG8_WAIT_L(0); PG8_BAR; PG8_MMA(1, 0, At, B0); PG8_MMA(1, 1, At, B1); PG8_BAR; PG8_SCHED;
;             PG8_LDB(B0, 1, 0); PG8_LDB(B1, 1, 1); PG8_SCHED; PG8_LDA(At, 1, 0); PG8_STAGE(PG8_SA(0, 1), a2 + hstepA, voffA);
;             PG8_WAIT_V(8); PG8_WAIT_L(0); PG8_BAR; PG8_MMA(0, 0, At, B0); PG8_MMA(0, 1, At, B1); PG8_BAR; PG8_SCHED;
.Lkw_pl_1:
	s_waitcnt lgkmcnt(0)
	s_barrier
	s_setprio 1
	s_waitcnt lgkmcnt(0)
	v_mfma_f32_16x16x32_bf16 v[60:63], v[148:151], v[208:211], v[60:63]
	v_mfma_f32_16x16x32_bf16 v[56:59], v[162:165], v[208:211], v[56:59]
	v_mfma_f32_16x16x32_bf16 v[44:47], v[148:151], v[216:219], v[44:47]
	v_mfma_f32_16x16x32_bf16 v[40:43], v[162:165], v[216:219], v[40:43]
	v_mfma_f32_16x16x32_bf16 v[28:31], v[148:151], v[224:227], v[28:31]
	v_mfma_f32_16x16x32_bf16 v[24:27], v[162:165], v[224:227], v[24:27]
	v_mfma_f32_16x16x32_bf16 v[12:15], v[148:151], v[232:235], v[12:15]
	v_mfma_f32_16x16x32_bf16 v[8:11], v[162:165], v[232:235], v[8:11]
	v_mfma_f32_16x16x32_bf16 v[60:63], v[158:161], v[212:215], v[60:63]
	v_mfma_f32_16x16x32_bf16 v[56:59], v[188:191], v[212:215], v[56:59]
	v_mfma_f32_16x16x32_bf16 v[44:47], v[158:161], v[220:223], v[44:47]
	v_mfma_f32_16x16x32_bf16 v[40:43], v[188:191], v[220:223], v[40:43]
	v_mfma_f32_16x16x32_bf16 v[28:31], v[158:161], v[228:231], v[28:31]
	v_mfma_f32_16x16x32_bf16 v[24:27], v[188:191], v[228:231], v[24:27]
	v_mfma_f32_16x16x32_bf16 v[12:15], v[158:161], v[236:239], v[12:15]
	v_mfma_f32_16x16x32_bf16 v[8:11], v[188:191], v[236:239], v[8:11]
	s_setprio 0
	s_setprio 1
	v_mfma_f32_16x16x32_bf16 v[52:55], v[192:195], v[208:211], v[52:55]
	v_mfma_f32_16x16x32_bf16 v[48:51], v[200:203], v[208:211], v[48:51]
	v_mfma_f32_16x16x32_bf16 v[36:39], v[192:195], v[216:219], v[36:39]
	v_mfma_f32_16x16x32_bf16 v[32:35], v[200:203], v[216:219], v[32:35]
	v_mfma_f32_16x16x32_bf16 v[20:23], v[192:195], v[224:227], v[20:23]
	v_mfma_f32_16x16x32_bf16 v[16:19], v[200:203], v[224:227], v[16:19]
	v_mfma_f32_16x16x32_bf16 v[4:7], v[192:195], v[232:235], v[4:7]
	v_mfma_f32_16x16x32_bf16 v[0:3], v[200:203], v[232:235], v[0:3]
	v_mfma_f32_16x16x32_bf16 v[52:55], v[196:199], v[212:215], v[52:55]
	v_mfma_f32_16x16x32_bf16 v[48:51], v[204:207], v[212:215], v[48:51]
	v_mfma_f32_16x16x32_bf16 v[36:39], v[196:199], v[220:223], v[36:39]
	v_mfma_f32_16x16x32_bf16 v[32:35], v[204:207], v[220:223], v[32:35]
	v_mfma_f32_16x16x32_bf16 v[20:23], v[196:199], v[228:231], v[20:23]
	v_mfma_f32_16x16x32_bf16 v[16:19], v[204:207], v[228:231], v[16:19]
	v_mfma_f32_16x16x32_bf16 v[4:7], v[196:199], v[236:239], v[4:7]
	v_mfma_f32_16x16x32_bf16 v[0:3], v[204:207], v[236:239], v[0:3]
	s_setprio 0
	s_barrier
	s_add_i32 s46, 0, 0x18000
	v_add_u32_e32 v128, s46, v155
	s_add_i32 s50, 0, 0x1c000
	ds_read_b128 v[148:151], v128
	ds_read_b128 v[158:161], v128 offset:1024
	ds_read_b128 v[162:165], v128 offset:2048
	ds_read_b128 v[188:191], v128 offset:3072
	v_add_u32_e32 v128, s50, v155
	ds_read_b128 v[192:195], v128
	ds_read_b128 v[196:199], v128 offset:1024
	ds_read_b128 v[200:203], v128 offset:2048
	ds_read_b128 v[204:207], v128 offset:3072
	s_add_u32 s48, s92, s84
	s_addc_u32 s49, s93, 0
	s_mov_b32 m0, s24
	v_lshl_add_u64 v[250:251], s[48:49], 0, v[136:137]
	ds_read_b128 v[208:211], v157 offset:32768
	ds_read_b128 v[212:215], v157 offset:33792
	ds_read_b128 v[216:219], v157 offset:34816
	ds_read_b128 v[220:223], v157 offset:35840
	ds_read_b128 v[224:227], v157 offset:36864
	ds_read_b128 v[228:231], v157 offset:37888
	ds_read_b128 v[232:235], v157 offset:38912
	ds_read_b128 v[236:239], v157 offset:39936
	global_load_lds_dwordx4 v[250:251], off
	v_lshl_add_u64 v[250:251], s[48:49], 0, v[140:141]
	s_mov_b32 m0, s25
	s_nop 0
	global_load_lds_dwordx4 v[250:251], off
	s_waitcnt vmcnt(8)
	s_waitcnt lgkmcnt(0)
	s_barrier
	s_setprio 1
	s_waitcnt lgkmcnt(0)
	v_mfma_f32_16x16x32_bf16 v[124:127], v[148:151], v[208:211], v[124:127]
	v_mfma_f32_16x16x32_bf16 v[120:123], v[162:165], v[208:211], v[120:123]
	v_mfma_f32_16x16x32_bf16 v[108:111], v[148:151], v[216:219], v[108:111]
	v_mfma_f32_16x16x32_bf16 v[104:107], v[162:165], v[216:219], v[104:107]
	v_mfma_f32_16x16x32_bf16 v[92:95], v[148:151], v[224:227], v[92:95]
	v_mfma_f32_16x16x32_bf16 v[88:91], v[162:165], v[224:227], v[88:91]
	v_mfma_f32_16x16x32_bf16 v[76:79], v[148:151], v[232:235], v[76:79]
	v_mfma_f32_16x16x32_bf16 v[72:75], v[162:165], v[232:235], v[72:75]
	v_mfma_f32_16x16x32_bf16 v[124:127], v[158:161], v[212:215], v[124:127]
	v_mfma_f32_16x16x32_bf16 v[120:123], v[188:191], v[212:215], v[120:123]
	v_mfma_f32_16x16x32_bf16 v[108:111], v[158:161], v[220:223], v[108:111]
	v_mfma_f32_16x16x32_bf16 v[104:107], v[188:191], v[220:223], v[104:107]
	v_mfma_f32_16x16x32_bf16 v[92:95], v[158:161], v[228:231], v[92:95]
	v_mfma_f32_16x16x32_bf16 v[88:91], v[188:191], v[228:231], v[88:91]
	v_mfma_f32_16x16x32_bf16 v[76:79], v[158:161], v[236:239], v[76:79]
	v_mfma_f32_16x16x32_bf16 v[72:75], v[188:191], v[236:239], v[72:75]
	s_setprio 0
	s_setprio 1
	v_mfma_f32_16x16x32_bf16 v[116:119], v[192:195], v[208:211], v[116:119]
	v_mfma_f32_16x16x32_bf16 v[112:115], v[200:203], v[208:211], v[112:115]
	v_mfma_f32_16x16x32_bf16 v[100:103], v[192:195], v[216:219], v[100:103]
	v_mfma_f32_16x16x32_bf16 v[96:99], v[200:203], v[216:219], v[96:99]
	v_mfma_f32_16x16x32_bf16 v[84:87], v[192:195], v[224:227], v[84:87]
	v_mfma_f32_16x16x32_bf16 v[80:83], v[200:203], v[224:227], v[80:83]
	v_mfma_f32_16x16x32_bf16 v[68:71], v[192:195], v[232:235], v[68:71]
	v_mfma_f32_16x16x32_bf16 v[64:67], v[200:203], v[232:235], v[64:67]
	v_mfma_f32_16x16x32_bf16 v[116:119], v[196:199], v[212:215], v[116:119]
	v_mfma_f32_16x16x32_bf16 v[112:115], v[204:207], v[212:215], v[112:115]
	v_mfma_f32_16x16x32_bf16 v[100:103], v[196:199], v[220:223], v[100:103]
	v_mfma_f32_16x16x32_bf16 v[96:99], v[204:207], v[220:223], v[96:99]
	v_mfma_f32_16x16x32_bf16 v[84:87], v[196:199], v[228:231], v[84:87]
	v_mfma_f32_16x16x32_bf16 v[80:83], v[204:207], v[228:231], v[80:83]
	v_mfma_f32_16x16x32_bf16 v[68:71], v[196:199], v[236:239], v[68:71]
	v_mfma_f32_16x16x32_bf16 v[64:67], v[204:207], v[236:239], v[64:67]
	s_setprio 0
	s_barrier
; #define PG8_STAGE(bufoff, gbase, voff) do { _Pragma("unroll") for (int _i = 0; _i < 2; ++_i) \
;         __builtin_amdgcn_global_load_lds((const unsigned*)((const char*)(gbase) + (voff)[_i]), (PG8_LAS unsigned*)(lds + (bufoff) + ldsw + _i * 8192), 16, 0, 0); } while (0)
; #define PG8_LDA(dst, b, h) do { _Pragma("unroll") for (int m = 0; m < 4; ++m) _Pragma("unroll") for (int k = 0; k < 2; ++k) dst[m][k] = *(const PG8_LAS bf16x8*)(lds + PG8_SA(b, h) + aoff + m * 2048 + k * 1024); } while (0)
; #define PG8_MMA(ai, bj, At, Bt) do { __builtin_amdgcn_s_setprio(1); _Pragma("unroll") for (int m = 0; m < 4; ++m) _Pragma("unroll") for (int n = 0; n < 2; ++n) _Pragma("unroll") for (int k = 0; k < 2; ++k) \
;         acc[ai][bj][m][n] = __builtin_amdgcn_mfma_f32_16x16x32_bf16(Bt[n][k], At[m][k], acc[ai][bj][m][n], 0, 0, 0); __builtin_amdgcn_s_setprio(0); } while (0)
; #define PG8_WAIT_V(n) asm volatile("s_waitcnt vmcnt(" #n ")" ::: "memory")
; #define PG8_WAIT_L(n) asm volatile("s_waitcnt lgkmcnt(" #n ")" ::: "memory")
; #define PG8_BAR __builtin_amdgcn_s_barrier()
; #define PG8_SCHED __builtin_amdgcn_sched_barrier(0)
; template <class Epi, class Sched, bool ALIGN_EPI = false, bool SP2 = false>
; __device__ __forceinline__ void gemm_phase(PG8_LAS unsigned char* lds, const Gemm g, const Sched& S, const Epi& E, const int tid) {
;     ...
;         for (int t = 0; t < nt; t += 2) {
;             const bool last = (t == nt - 2);
;             const char* a1 = cA + (size_t)(t + 1) * kstep;
;             const char* a2 = last ? nA : cA + (size_t)(t + 2) * kstep; const char* b2 = last ? nB : cB + (size_t)(t + 2) * kstep;
;             const char* a3 = a2 + kstep; const char* b3 = b2 + kstep;
;             if (last && has_next) S.a_ready(nxt);
;     ...
;             PG8_LDA(At, 1, 1); PG8_STAGE(PG8_SB(1, 0), b3, voffB); PG8_STAGE(PG8_SB(1, 1), b3 + hstepB, voffB); PG8_STAGE(PG8_SA(1, 0), a3, voffA);
;             PG8_WAIT_V(8); PG8_WAIT_L(0); PG8_BAR; PG8_MMA(1, 0, At, B0); PG8_MMA(1, 1, At, B1); PG8_BAR; PG8_SCHED;
	s_add_i32 s46, s46, s81
	v_lshl_add_u64 v[166:167], v[166:167], 0, s[76:77]
	s_mov_b32 m0, s46
	ds_read_b128 v[208:211], v157 offset:49152
	ds_read_b128 v[212:215], v157 offset:50176
	ds_read_b128 v[216:219], v157 offset:51200
	ds_read_b128 v[220:223], v157 offset:52224
	ds_read_b128 v[224:227], v157 offset:53248
	ds_read_b128 v[228:231], v157 offset:54272
	ds_read_b128 v[232:235], v157 offset:55296
	ds_read_b128 v[236:239], v157 offset:56320
	global_load_lds_dwordx4 v[166:167], off
	v_lshl_add_u64 v[166:167], v[240:241], 0, s[76:77]
	s_add_i32 m0, s46, 0x2000
	s_add_i32 s46, s50, s81
	global_load_lds_dwordx4 v[166:167], off
	v_lshl_add_u64 v[166:167], v[242:243], 0, s[76:77]
	s_mov_b32 m0, s46
	s_nop 0
	global_load_lds_dwordx4 v[166:167], off
	v_lshl_add_u64 v[166:167], v[244:245], 0, s[76:77]
	s_add_i32 m0, s46, 0x2000
	s_nop 0
	global_load_lds_dwordx4 v[166:167], off
	v_lshl_add_u64 v[166:167], v[246:247], 0, s[76:77]
	s_mov_b32 m0, s27
	s_nop 0
	global_load_lds_dwordx4 v[166:167], off
	v_lshl_add_u64 v[166:167], v[248:249], 0, s[76:77]
	s_mov_b32 m0, s28
	s_nop 0
	global_load_lds_dwordx4 v[166:167], off
	s_waitcnt vmcnt(8)
	s_waitcnt lgkmcnt(0)
	s_barrier
	s_setprio 1
	s_waitcnt lgkmcnt(0)
	v_mfma_f32_16x16x32_bf16 v[60:63], v[148:151], v[208:211], v[60:63]
	v_mfma_f32_16x16x32_bf16 v[56:59], v[162:165], v[208:211], v[56:59]
	v_mfma_f32_16x16x32_bf16 v[44:47], v[148:151], v[216:219], v[44:47]
	v_mfma_f32_16x16x32_bf16 v[40:43], v[162:165], v[216:219], v[40:43]
	v_mfma_f32_16x16x32_bf16 v[28:31], v[148:151], v[224:227], v[28:31]
	v_mfma_f32_16x16x32_bf16 v[24:27], v[162:165], v[224:227], v[24:27]
	v_mfma_f32_16x16x32_bf16 v[12:15], v[148:151], v[232:235], v[12:15]
	v_mfma_f32_16x16x32_bf16 v[8:11], v[162:165], v[232:235], v[8:11]
	v_mfma_f32_16x16x32_bf16 v[60:63], v[158:161], v[212:215], v[60:63]
	v_mfma_f32_16x16x32_bf16 v[56:59], v[188:191], v[212:215], v[56:59]
	v_mfma_f32_16x16x32_bf16 v[44:47], v[158:161], v[220:223], v[44:47]
	v_mfma_f32_16x16x32_bf16 v[40:43], v[188:191], v[220:223], v[40:43]
	v_mfma_f32_16x16x32_bf16 v[28:31], v[158:161], v[228:231], v[28:31]
	v_mfma_f32_16x16x32_bf16 v[24:27], v[188:191], v[228:231], v[24:27]
	v_mfma_f32_16x16x32_bf16 v[12:15], v[158:161], v[236:239], v[12:15]
	v_mfma_f32_16x16x32_bf16 v[8:11], v[188:191], v[236:239], v[8:11]
	s_setprio 0
	s_setprio 1
	v_mfma_f32_16x16x32_bf16 v[52:55], v[192:195], v[208:211], v[52:55]
	v_mfma_f32_16x16x32_bf16 v[48:51], v[200:203], v[208:211], v[48:51]
	v_mfma_f32_16x16x32_bf16 v[36:39], v[192:195], v[216:219], v[36:39]
	v_mfma_f32_16x16x32_bf16 v[32:35], v[200:203], v[216:219], v[32:35]
	v_mfma_f32_16x16x32_bf16 v[20:23], v[192:195], v[224:227], v[20:23]
	v_mfma_f32_16x16x32_bf16 v[16:19], v[200:203], v[224:227], v[16:19]
	v_mfma_f32_16x16x32_bf16 v[4:7], v[192:195], v[232:235], v[4:7]
	v_mfma_f32_16x16x32_bf16 v[0:3], v[200:203], v[232:235], v[0:3]
	v_mfma_f32_16x16x32_bf16 v[52:55], v[196:199], v[212:215], v[52:55]
	v_mfma_f32_16x16x32_bf16 v[48:51], v[204:207], v[212:215], v[48:51]
	v_mfma_f32_16x16x32_bf16 v[36:39], v[196:199], v[220:223], v[36:39]
	v_mfma_f32_16x16x32_bf16 v[32:35], v[204:207], v[220:223], v[32:35]
	v_mfma_f32_16x16x32_bf16 v[20:23], v[196:199], v[228:231], v[20:23]
	v_mfma_f32_16x16x32_bf16 v[16:19], v[204:207], v[228:231], v[16:19]
	v_mfma_f32_16x16x32_bf16 v[4:7], v[196:199], v[236:239], v[4:7]
	v_mfma_f32_16x16x32_bf16 v[0:3], v[204:207], v[236:239], v[0:3]
	s_setprio 0
	s_add_u32 s8, s8, 0x100
	s_addc_u32 s9, s9, 0
	s_add_u32 s44, s44, 0x100
	s_addc_u32 s45, s45, 0
	s_cmp_ge_u32 s47, s14
	s_mov_b32 s46, s47
	s_cbranch_scc1 .Lkl_pl_exit
	s_add_i32 s47, s46, 2
	s_add_u32 s48, s8, 0x80
	s_addc_u32 s49, s9, 0
	s_add_i32 s50, 0, 0x10000
	s_cmp_eq_u32 s30, s46
	s_cselect_b32 s93, s75, s49
	s_cselect_b32 s92, s74, s48
	s_cselect_b32 s49, s42, s45
	s_cselect_b32 s48, s43, s44
	s_cmp_eq_u32 s47, 2
	s_cselect_b32 s99, 1, 0
	s_cmp_eq_u32 s29, 1
	s_cselect_b32 s99, 0, s99
	s_add_i32 s46, 0, 0x14000
	s_barrier
	s_branch .Lkl_pl_body
.Lkl_pl_exit:
	s_barrier
	s_and_b64 vcc, exec, s[22:23]
	s_cbranch_vccz .LBB0_471
	s_barrier
